# v20: v15 + cooperative grid sync removed + hand-scheduled attention softmax/PV block (permlane-swap row max, in-place P, prefetched V fragments), no ping-pong
# speedup vs baseline: 1.0078x; 1.0056x over previous
; __global__ void __launch_bounds__(512, 2) mk_fwd(Params p) {
;     ...
;     if (ph_hi - ph_lo > 1) {
;         xbar = xcd_barrier_post((unsigned*)KARG_WS, bst);
;         grid.sync();
;     }
;     int rep = 0;
;     for (int ph = ph_lo; ph < ph_hi;) {
.LBB0_5:
	s_or_b64 exec, exec, s[2:3]
	v_lshrrev_b32_e32 v1, 20, v0
	v_lshrrev_b32_e32 v0, 10, v0
	v_or_b32_e32 v0, v0, v1
	s_movk_i32 s2, 0x3ff
	v_and_or_b32 v0, v0, s2, v179
	v_cmp_eq_u32_e32 vcc, 0, v0
	s_waitcnt lgkmcnt(0)
	s_barrier
	s_and_saveexec_b64 s[2:3], vcc
.LBB0_15:
	s_or_b64 exec, exec, s[2:3]
	s_barrier
	s_cmp_le_i32 s56, s53
	s_cbranch_scc0 .LBB0_17
	s_branch .LBB0_412

; #define LAS __attribute__((address_space(3)))
; __device__ __forceinline__ void attn_phase(LAS unsigned char* lds, const bf16_t* Q, const bf16_t* KN, const bf16_t* P, const bf16_t* VT, bf16_t* CAT, int bid, int G, const int tid) {
;     ...
;                 for (int qi = 0; qi < 2; ++qi) {
;                     float mx = -INFINITY;
; #pragma unroll
;                     for (int kb = 0; kb < 4; ++kb) mx = fmaxf(mx, fmaxf(fmaxf(s[kb][qi][0], s[kb][qi][1]), fmaxf(s[kb][qi][2], s[kb][qi][3])));
;                     mx = fmaxf(mx, __shfl_xor(mx, 16)); mx = fmaxf(mx, __shfl_xor(mx, 32));
;                     const float mnew = fmaxf(mrow[qi], mx);
;                     const float alpha = __builtin_amdgcn_exp2f(mrow[qi] - mnew);
;                     mrow[qi] = mnew;
;                     float ps = 0.f;
; #pragma unroll
;                     for (int kb = 0; kb < 4; ++kb)
; #pragma unroll
;                         for (int j = 0; j < 4; ++j) { const float e = __builtin_amdgcn_exp2f(s[kb][qi][j] - mnew); s[kb][qi][j] = e; ps += e; }
;                     lrow[qi] = lrow[qi] * alpha + ps;
; #pragma unroll
;                     for (int d = 0; d < 8; ++d) o[d][qi] = o[d][qi] * alpha;
; #pragma unroll
;                     for (int cc = 0; cc < 2; ++cc) {
;                         u32x4 t; t.x = cvt_pk_bf16(s[2 * cc][qi][0], s[2 * cc][qi][1]); t.y = cvt_pk_bf16(s[2 * cc][qi][2], s[2 * cc][qi][3]);
;                         t.z = cvt_pk_bf16(s[2 * cc + 1][qi][0], s[2 * cc + 1][qi][1]); t.w = cvt_pk_bf16(s[2 * cc + 1][qi][2], s[2 * cc + 1][qi][3]);
;                         pf[qi][cc] = __builtin_bit_cast(bf16x8, t);
;                     }
;                 }
; #pragma unroll
;                 for (int cc = 0; cc < 2; ++cc)
; #pragma unroll
;                     for (int d = 0; d < 8; ++d) {
;                         const LAS unsigned char* vp = buf + KBYTES + ((d * 16 + fr) * VS + 32 * cc + 4 * fq) * 2;
;                         const u32x2 v0 = *(const LAS u32x2*)vp, v1 = *(const LAS u32x2*)(vp + 32);
;                         const u32x4 vv = {v0.x, v0.y, v1.x, v1.y};
;                         const bf16x8 vf = __builtin_bit_cast(bf16x8, vv);
;                         o[d][0] = __builtin_amdgcn_mfma_f32_16x16x32_bf16(vf, pf[0][cc], o[d][0], 0, 0, 0);
;                         o[d][1] = __builtin_amdgcn_mfma_f32_16x16x32_bf16(vf, pf[1][cc], o[d][1], 0, 0, 0);
.LBB0_144:
	v_add3_u32 v174, s35, v180, v243
	v_add_u32_e32 v175, 0x6400, v174
	ds_read2_b64 v[208:211], v175 offset1:4
	v_add_u32_e32 v172, 0x6d00, v174
	ds_read2_b64 v[212:215], v172 offset1:4
	v_add_u32_e32 v173, 0x7600, v174
	ds_read2_b64 v[216:219], v173 offset1:4
	v_add_u32_e32 v175, 0x7f00, v174
	ds_read2_b64 v[220:223], v175 offset1:4
	v_add_u32_e32 v172, 0x8800, v174
	ds_read2_b64 v[224:227], v172 offset1:4
	v_max3_f32 v170, v132, v133, v134
	v_max3_f32 v204, v148, v149, v150
	v_max3_f32 v171, v135, v136, v137
	v_max3_f32 v205, v151, v156, v157
	v_max3_f32 v170, v170, v138, v139
	v_max3_f32 v204, v204, v158, v159
	v_max3_f32 v171, v171, v140, v141
	v_max3_f32 v205, v205, v152, v153
	v_max3_f32 v170, v170, v142, v143
	v_max3_f32 v204, v204, v154, v155
	v_max3_f32 v171, v171, v144, v145
	v_max3_f32 v205, v205, v160, v161
	v_max3_f32 v170, v170, v146, v147
	v_max3_f32 v204, v204, v162, v163
	v_max_f32_e32 v170, v170, v171
	v_max_f32_e32 v204, v204, v205
	v_mov_b32_e32 v171, v170
	v_mov_b32_e32 v205, v204
	s_nop 1
	v_permlane16_swap_b32 v170, v171
	v_permlane16_swap_b32 v204, v205
	v_max_f32_e32 v170, v170, v171
	v_max_f32_e32 v204, v204, v205
	v_mov_b32_e32 v171, v170
	v_mov_b32_e32 v205, v204
	s_nop 1
	v_permlane32_swap_b32 v170, v171
	v_permlane32_swap_b32 v204, v205
	v_max3_f32 v245, v207, v170, v171
	v_max3_f32 v246, v206, v204, v205
	v_sub_f32_e32 v171, v207, v245
	v_sub_f32_e32 v205, v206, v246
	v_exp_f32_e32 v230, v171
	v_exp_f32_e32 v252, v205
	v_pk_add_f32 v[132:133], v[132:133], v[244:245] op_sel:[0,1] op_sel_hi:[1,1] neg_lo:[0,1] neg_hi:[0,1]
	v_pk_add_f32 v[148:149], v[148:149], v[246:247] op_sel_hi:[1,0] neg_lo:[0,1] neg_hi:[0,1]
	v_pk_add_f32 v[134:135], v[134:135], v[244:245] op_sel:[0,1] op_sel_hi:[1,1] neg_lo:[0,1] neg_hi:[0,1]
	v_pk_add_f32 v[150:151], v[150:151], v[246:247] op_sel_hi:[1,0] neg_lo:[0,1] neg_hi:[0,1]
	v_pk_add_f32 v[136:137], v[136:137], v[244:245] op_sel:[0,1] op_sel_hi:[1,1] neg_lo:[0,1] neg_hi:[0,1]
	v_pk_add_f32 v[156:157], v[156:157], v[246:247] op_sel_hi:[1,0] neg_lo:[0,1] neg_hi:[0,1]
	v_pk_add_f32 v[138:139], v[138:139], v[244:245] op_sel:[0,1] op_sel_hi:[1,1] neg_lo:[0,1] neg_hi:[0,1]
	v_pk_add_f32 v[158:159], v[158:159], v[246:247] op_sel_hi:[1,0] neg_lo:[0,1] neg_hi:[0,1]
	v_exp_f32_e32 v132, v132
	v_exp_f32_e32 v148, v148
	v_exp_f32_e32 v133, v133
	v_exp_f32_e32 v149, v149
	v_exp_f32_e32 v134, v134
	v_exp_f32_e32 v150, v150
	v_exp_f32_e32 v135, v135
	v_exp_f32_e32 v151, v151
	v_exp_f32_e32 v136, v136
	v_exp_f32_e32 v156, v156
	v_exp_f32_e32 v137, v137
	v_exp_f32_e32 v157, v157
	v_exp_f32_e32 v138, v138
	v_exp_f32_e32 v158, v158
	v_exp_f32_e32 v139, v139
	v_exp_f32_e32 v159, v159
	v_pk_mul_f32 v[32:33], v[32:33], v[230:231] op_sel_hi:[1,0]
	v_pk_mul_f32 v[34:35], v[34:35], v[230:231] op_sel_hi:[1,0]
	v_pk_mul_f32 v[0:1], v[0:1], v[252:253] op_sel_hi:[1,0]
	v_pk_mul_f32 v[2:3], v[2:3], v[252:253] op_sel_hi:[1,0]
	v_pk_add_f32 v[228:229], v[132:133], v[134:135]
	v_pk_add_f32 v[170:171], v[148:149], v[150:151]
	v_pk_add_f32 v[228:229], v[228:229], v[136:137]
	v_pk_add_f32 v[170:171], v[170:171], v[156:157]
	v_pk_add_f32 v[228:229], v[228:229], v[138:139]
	v_pk_add_f32 v[170:171], v[170:171], v[158:159]
	v_cvt_pk_bf16_f32 v132, v132, v133
	v_cvt_pk_bf16_f32 v133, v134, v135
	v_cvt_pk_bf16_f32 v134, v136, v137
	v_cvt_pk_bf16_f32 v135, v138, v139
	v_cvt_pk_bf16_f32 v148, v148, v149
	v_cvt_pk_bf16_f32 v149, v150, v151
	v_cvt_pk_bf16_f32 v150, v156, v157
	v_cvt_pk_bf16_f32 v151, v158, v159
	v_add_u32_e32 v173, 0x9100, v174
	ds_read2_b64 v[136:139], v173 offset1:4
	v_add_u32_e32 v175, 0x9a00, v174
	ds_read2_b64 v[156:159], v175 offset1:4
	v_pk_mul_f32 v[36:37], v[36:37], v[230:231] op_sel_hi:[1,0]
	v_pk_mul_f32 v[38:39], v[38:39], v[230:231] op_sel_hi:[1,0]
	v_pk_mul_f32 v[4:5], v[4:5], v[252:253] op_sel_hi:[1,0]
	v_pk_mul_f32 v[6:7], v[6:7], v[252:253] op_sel_hi:[1,0]
	s_waitcnt lgkmcnt(6)
	v_mfma_f32_16x16x32_bf16 v[32:35], v[208:211], v[132:135], v[32:35]
	v_mfma_f32_16x16x32_bf16 v[0:3], v[208:211], v[148:151], v[0:3]
	v_add_u32_e32 v172, 0xa300, v174
	ds_read2_b64 v[208:211], v172 offset1:4
	v_pk_mul_f32 v[40:41], v[40:41], v[230:231] op_sel_hi:[1,0]
	v_pk_mul_f32 v[42:43], v[42:43], v[230:231] op_sel_hi:[1,0]
	v_pk_mul_f32 v[8:9], v[8:9], v[252:253] op_sel_hi:[1,0]
	v_pk_mul_f32 v[10:11], v[10:11], v[252:253] op_sel_hi:[1,0]
	v_pk_add_f32 v[140:141], v[140:141], v[244:245] op_sel:[0,1] op_sel_hi:[1,1] neg_lo:[0,1] neg_hi:[0,1]
	v_pk_add_f32 v[152:153], v[152:153], v[246:247] op_sel_hi:[1,0] neg_lo:[0,1] neg_hi:[0,1]
	v_pk_add_f32 v[142:143], v[142:143], v[244:245] op_sel:[0,1] op_sel_hi:[1,1] neg_lo:[0,1] neg_hi:[0,1]
	v_pk_add_f32 v[154:155], v[154:155], v[246:247] op_sel_hi:[1,0] neg_lo:[0,1] neg_hi:[0,1]
	v_pk_add_f32 v[144:145], v[144:145], v[244:245] op_sel:[0,1] op_sel_hi:[1,1] neg_lo:[0,1] neg_hi:[0,1]
	v_pk_add_f32 v[160:161], v[160:161], v[246:247] op_sel_hi:[1,0] neg_lo:[0,1] neg_hi:[0,1]
	s_waitcnt lgkmcnt(6)
; #define LAS __attribute__((address_space(3)))
; __device__ __forceinline__ unsigned cvt_pk_bf16(float lo, float hi) { unsigned r; asm("v_cvt_pk_bf16_f32 %0, %1, %2" : "=v"(r) : "v"(lo), "v"(hi)); return r; }
; __device__ __forceinline__ void attn_phase(LAS unsigned char* lds, const bf16_t* Q, const bf16_t* KN, const bf16_t* P, const bf16_t* VT, bf16_t* CAT, int bid, int G, const int tid) {
;     ...
;                     for (int kb = 0; kb < 4; ++kb)
; #pragma unroll
;                         for (int j = 0; j < 4; ++j) { const float e = __builtin_amdgcn_exp2f(s[kb][qi][j] - mnew); s[kb][qi][j] = e; ps += e; }
;                     lrow[qi] = lrow[qi] * alpha + ps;
; #pragma unroll
;                     for (int d = 0; d < 8; ++d) o[d][qi] = o[d][qi] * alpha;
; #pragma unroll
;                     for (int cc = 0; cc < 2; ++cc) {
;                         u32x4 t; t.x = cvt_pk_bf16(s[2 * cc][qi][0], s[2 * cc][qi][1]); t.y = cvt_pk_bf16(s[2 * cc][qi][2], s[2 * cc][qi][3]);
;                         t.z = cvt_pk_bf16(s[2 * cc + 1][qi][0], s[2 * cc + 1][qi][1]); t.w = cvt_pk_bf16(s[2 * cc + 1][qi][2], s[2 * cc + 1][qi][3]);
;                         pf[qi][cc] = __builtin_bit_cast(bf16x8, t);
;                     }
;                 }
; #pragma unroll
;                 for (int cc = 0; cc < 2; ++cc)
; #pragma unroll
;                     for (int d = 0; d < 8; ++d) {
;                         const LAS unsigned char* vp = buf + KBYTES + ((d * 16 + fr) * VS + 32 * cc + 4 * fq) * 2;
;                         const u32x2 v0 = *(const LAS u32x2*)vp, v1 = *(const LAS u32x2*)(vp + 32);
;                         const u32x4 vv = {v0.x, v0.y, v1.x, v1.y};
;                         const bf16x8 vf = __builtin_bit_cast(bf16x8, vv);
;                         o[d][0] = __builtin_amdgcn_mfma_f32_16x16x32_bf16(vf, pf[0][cc], o[d][0], 0, 0, 0);
;                         o[d][1] = __builtin_amdgcn_mfma_f32_16x16x32_bf16(vf, pf[1][cc], o[d][1], 0, 0, 0);
	v_mfma_f32_16x16x32_bf16 v[36:39], v[212:215], v[132:135], v[36:39]
	v_mfma_f32_16x16x32_bf16 v[4:7], v[212:215], v[148:151], v[4:7]
	v_add_u32_e32 v173, 0x6400, v174
	ds_read2_b64 v[212:215], v173 offset0:8 offset1:12
	v_pk_mul_f32 v[44:45], v[44:45], v[230:231] op_sel_hi:[1,0]
	v_pk_mul_f32 v[46:47], v[46:47], v[230:231] op_sel_hi:[1,0]
	v_pk_mul_f32 v[12:13], v[12:13], v[252:253] op_sel_hi:[1,0]
	v_pk_mul_f32 v[14:15], v[14:15], v[252:253] op_sel_hi:[1,0]
	v_pk_add_f32 v[146:147], v[146:147], v[244:245] op_sel:[0,1] op_sel_hi:[1,1] neg_lo:[0,1] neg_hi:[0,1]
	v_pk_add_f32 v[162:163], v[162:163], v[246:247] op_sel_hi:[1,0] neg_lo:[0,1] neg_hi:[0,1]
	v_exp_f32_e32 v140, v140
	v_exp_f32_e32 v152, v152
	v_exp_f32_e32 v141, v141
	v_exp_f32_e32 v153, v153
	s_waitcnt lgkmcnt(6)
	v_mfma_f32_16x16x32_bf16 v[40:43], v[216:219], v[132:135], v[40:43]
	v_mfma_f32_16x16x32_bf16 v[8:11], v[216:219], v[148:151], v[8:11]
	v_add_u32_e32 v175, 0x6d00, v174
	ds_read2_b64 v[216:219], v175 offset0:8 offset1:12
	v_pk_mul_f32 v[52:53], v[52:53], v[230:231] op_sel_hi:[1,0]
	v_pk_mul_f32 v[54:55], v[54:55], v[230:231] op_sel_hi:[1,0]
	v_pk_mul_f32 v[16:17], v[16:17], v[252:253] op_sel_hi:[1,0]
	v_pk_mul_f32 v[18:19], v[18:19], v[252:253] op_sel_hi:[1,0]
	v_exp_f32_e32 v142, v142
	v_exp_f32_e32 v154, v154
	v_exp_f32_e32 v143, v143
	v_exp_f32_e32 v155, v155
	v_exp_f32_e32 v144, v144
	v_exp_f32_e32 v160, v160
	s_waitcnt lgkmcnt(6)
	v_mfma_f32_16x16x32_bf16 v[44:47], v[220:223], v[132:135], v[44:47]
	v_mfma_f32_16x16x32_bf16 v[12:15], v[220:223], v[148:151], v[12:15]
	v_add_u32_e32 v172, 0x7600, v174
	ds_read2_b64 v[220:223], v172 offset0:8 offset1:12
	v_pk_mul_f32 v[48:49], v[48:49], v[230:231] op_sel_hi:[1,0]
	v_pk_mul_f32 v[50:51], v[50:51], v[230:231] op_sel_hi:[1,0]
	v_pk_mul_f32 v[20:21], v[20:21], v[252:253] op_sel_hi:[1,0]
	v_pk_mul_f32 v[22:23], v[22:23], v[252:253] op_sel_hi:[1,0]
	v_exp_f32_e32 v145, v145
	v_exp_f32_e32 v161, v161
	v_exp_f32_e32 v146, v146
	v_exp_f32_e32 v162, v162
	v_exp_f32_e32 v147, v147
	v_exp_f32_e32 v163, v163
	s_waitcnt lgkmcnt(6)
	v_mfma_f32_16x16x32_bf16 v[52:55], v[224:227], v[132:135], v[52:55]
	v_mfma_f32_16x16x32_bf16 v[16:19], v[224:227], v[148:151], v[16:19]
	v_add_u32_e32 v173, 0x7f00, v174
	ds_read2_b64 v[224:227], v173 offset0:8 offset1:12
	v_pk_mul_f32 v[56:57], v[56:57], v[230:231] op_sel_hi:[1,0]
	v_pk_mul_f32 v[58:59], v[58:59], v[230:231] op_sel_hi:[1,0]
	v_pk_mul_f32 v[24:25], v[24:25], v[252:253] op_sel_hi:[1,0]
	v_pk_mul_f32 v[26:27], v[26:27], v[252:253] op_sel_hi:[1,0]
	v_pk_add_f32 v[228:229], v[228:229], v[140:141]
	v_pk_add_f32 v[170:171], v[170:171], v[152:153]
	v_pk_add_f32 v[228:229], v[228:229], v[142:143]
	v_pk_add_f32 v[170:171], v[170:171], v[154:155]
	v_pk_add_f32 v[228:229], v[228:229], v[144:145]
	v_pk_add_f32 v[170:171], v[170:171], v[160:161]
	s_waitcnt lgkmcnt(6)
	v_mfma_f32_16x16x32_bf16 v[48:51], v[136:139], v[132:135], v[48:51]
	v_mfma_f32_16x16x32_bf16 v[20:23], v[136:139], v[148:151], v[20:23]
	v_add_u32_e32 v175, 0x8800, v174
	ds_read2_b64 v[136:139], v175 offset0:8 offset1:12
	v_pk_mul_f32 v[60:61], v[60:61], v[230:231] op_sel_hi:[1,0]
	v_pk_mul_f32 v[62:63], v[62:63], v[230:231] op_sel_hi:[1,0]
	v_pk_mul_f32 v[28:29], v[28:29], v[252:253] op_sel_hi:[1,0]
	v_pk_mul_f32 v[30:31], v[30:31], v[252:253] op_sel_hi:[1,0]
	v_pk_add_f32 v[228:229], v[228:229], v[146:147]
	v_pk_add_f32 v[170:171], v[170:171], v[162:163]
	v_add_f32_e32 v228, v228, v229
	v_add_f32_e32 v170, v170, v171
	v_cvt_pk_bf16_f32 v140, v140, v141
	v_cvt_pk_bf16_f32 v141, v142, v143
	s_waitcnt lgkmcnt(6)
	v_mfma_f32_16x16x32_bf16 v[56:59], v[156:159], v[132:135], v[56:59]
	v_mfma_f32_16x16x32_bf16 v[24:27], v[156:159], v[148:151], v[24:27]
	v_add_u32_e32 v172, 0x9100, v174
	ds_read2_b64 v[156:159], v172 offset0:8 offset1:12
	v_cvt_pk_bf16_f32 v142, v144, v145
	v_cvt_pk_bf16_f32 v143, v146, v147
	v_cvt_pk_bf16_f32 v152, v152, v153
	v_cvt_pk_bf16_f32 v153, v154, v155
	v_cvt_pk_bf16_f32 v154, v160, v161
	v_cvt_pk_bf16_f32 v155, v162, v163
	s_waitcnt lgkmcnt(6)
	v_mfma_f32_16x16x32_bf16 v[60:63], v[208:211], v[132:135], v[60:63]
	v_mfma_f32_16x16x32_bf16 v[28:31], v[208:211], v[148:151], v[28:31]
	v_add_u32_e32 v173, 0x9a00, v174
	ds_read2_b64 v[208:211], v173 offset0:8 offset1:12
	v_fma_f32 v203, v203, v230, v228
	v_fma_f32 v202, v202, v252, v170
	v_mov_b32_e32 v207, v245
	v_mov_b32_e32 v206, v246
	s_waitcnt lgkmcnt(6)
	v_mfma_f32_16x16x32_bf16 v[32:35], v[212:215], v[140:143], v[32:35]
	v_mfma_f32_16x16x32_bf16 v[0:3], v[212:215], v[152:155], v[0:3]
	v_add_u32_e32 v175, 0xa300, v174
	ds_read2_b64 v[212:215], v175 offset0:8 offset1:12
	s_waitcnt lgkmcnt(6)
	v_mfma_f32_16x16x32_bf16 v[36:39], v[216:219], v[140:143], v[36:39]
	v_mfma_f32_16x16x32_bf16 v[4:7], v[216:219], v[152:155], v[4:7]
	s_waitcnt lgkmcnt(5)
	v_mfma_f32_16x16x32_bf16 v[40:43], v[220:223], v[140:143], v[40:43]
	v_mfma_f32_16x16x32_bf16 v[8:11], v[220:223], v[152:155], v[8:11]
	s_waitcnt lgkmcnt(4)
	v_mfma_f32_16x16x32_bf16 v[44:47], v[224:227], v[140:143], v[44:47]
	v_mfma_f32_16x16x32_bf16 v[12:15], v[224:227], v[152:155], v[12:15]
	s_waitcnt lgkmcnt(3)
	v_mfma_f32_16x16x32_bf16 v[52:55], v[136:139], v[140:143], v[52:55]
	v_mfma_f32_16x16x32_bf16 v[16:19], v[136:139], v[152:155], v[16:19]
	s_waitcnt lgkmcnt(2)
	v_mfma_f32_16x16x32_bf16 v[48:51], v[156:159], v[140:143], v[48:51]
	v_mfma_f32_16x16x32_bf16 v[20:23], v[156:159], v[152:155], v[20:23]
	s_waitcnt lgkmcnt(1)
	v_mfma_f32_16x16x32_bf16 v[56:59], v[208:211], v[140:143], v[56:59]
	v_mfma_f32_16x16x32_bf16 v[24:27], v[208:211], v[152:155], v[24:27]
	s_waitcnt lgkmcnt(0)
	v_mfma_f32_16x16x32_bf16 v[60:63], v[212:215], v[140:143], v[60:63]
	v_mfma_f32_16x16x32_bf16 v[28:31], v[212:215], v[152:155], v[28:31]

; #define LAS __attribute__((address_space(3)))
; __device__ __forceinline__ void attn_phase(LAS unsigned char* lds, const bf16_t* Q, const bf16_t* KN, const bf16_t* P, const bf16_t* VT, bf16_t* CAT, int bid, int G, const int tid) {
;     ...
;         for (int kt = 0; kt < nt; ++kt) {
;             LAS unsigned char* buf = lds + (kt & 1) * BUFB;
;             *(LAS u32x4*)(buf + lk) = rk0; *(LAS u32x4*)(buf + lk + 32 * KS * 2) = rk1; *(LAS u32x4*)(buf + lp) = rp;
;             *(LAS u32x4*)(buf + lv) = rv0; *(LAS u32x4*)(buf + lv + 64 * VS * 2) = rv1;
;             __syncthreads();
;             if (kt + 1 < nt) {
;                 const size_t ko = (size_t)(kt + 1) * 64;
;                 rk0 = *(const u32x4*)(gk + ko * 1024); rk1 = *(const u32x4*)(gk + (ko + 32) * 1024); rp = *(const u32x4*)(gp + ko * P_LD);
;                 rv0 = *(const u32x4*)(gv + ko); rv1 = *(const u32x4*)(gv + (size_t)64 * M + ko);
;             }
;             if (kt * 64 <= qlo + 31) {
;                 f32x4 s[4][2];
; #pragma unroll
;                 for (int kb = 0; kb < 4; ++kb) { s[kb][0] = (f32x4){0.f, 0.f, 0.f, 0.f}; s[kb][1] = (f32x4){0.f, 0.f, 0.f, 0.f}; }
; #pragma unroll
;                 for (int ch = 0; ch < 6; ++ch) {
; #pragma unroll
;                     for (int kb = 0; kb < 4; ++kb) {
;                         const bf16x8 kf = *(const LAS bf16x8*)(buf + ((kb * 16 + fr) * KS + ch * 32 + fq * 8) * 2);
;                         s[kb][0] = __builtin_amdgcn_mfma_f32_16x16x32_bf16(kf, qf[0][ch], s[kb][0], 0, 0, 0);
;                         s[kb][1] = __builtin_amdgcn_mfma_f32_16x16x32_bf16(kf, qf[1][ch], s[kb][1], 0, 0, 0);
;                     }
;                     if (ch & 1) asm volatile("" ::: "memory");
;                 }
.LBB0_146:
	s_bitcmp1_b32 s34, 0
	s_cselect_b32 s4, 0xac00, 0
	s_add_i32 s35, s4, 0
	v_add_u32_e32 v132, s35, v183
	s_waitcnt vmcnt(0) lgkmcnt(0)
	ds_write_b128 v132, v[112:115]
	ds_write_b128 v132, v[116:119] offset:12800
	v_add_u32_e32 v112, s35, v240
	ds_write_b128 v112, v[120:123]
	v_add_u32_e32 v112, s35, v241
	ds_write_b128 v112, v[124:127] offset:25600
	ds_write_b128 v112, v[128:131] offset:34816
	v_lshl_add_u64 v[112:113], s[24:25], 0, v[166:167]
	s_mov_b32 s4, 0x1c220000
	v_add_co_u32_e32 v114, vcc, s4, v112
	s_mov_b32 s4, 0x1c230000
	s_nop 0
	v_addc_co_u32_e32 v115, vcc, 0, v113, vcc
	v_add_co_u32_e32 v116, vcc, s4, v112
	v_lshl_add_u64 v[128:129], s[24:25], 0, v[168:169]
	s_nop 0
	v_addc_co_u32_e32 v117, vcc, 0, v113, vcc
	v_add_co_u32_e32 v124, vcc, 0x20200000, v128
	v_lshl_add_u64 v[120:121], s[24:25], 0, v[164:165]
	s_nop 0
	v_addc_co_u32_e32 v125, vcc, 0, v129, vcc
	v_add_co_u32_e32 v128, vcc, 0x20600000, v128
	s_waitcnt lgkmcnt(0)
	s_nop 0
	v_addc_co_u32_e32 v129, vcc, 0, v129, vcc
	s_barrier
	global_load_dwordx4 v[112:115], v[114:115], off
	s_nop 0
	global_load_dwordx4 v[116:119], v[116:117], off
	s_nop 0
	global_load_dwordx4 v[120:123], v[120:121], off
	s_nop 0
	global_load_dwordx4 v[124:127], v[124:125], off offset:128
	s_cmp_gt_i32 s30, s26
	global_load_dwordx4 v[128:131], v[128:129], off offset:128
	s_cbranch_scc1 .LBB0_145
	v_add3_u32 v174, s35, v182, v181
	ds_read_b128 v[170:173], v174
	ds_read_b128 v[208:211], v174 offset:6400
	ds_read_b128 v[212:215], v174 offset:12800
	ds_read_b128 v[216:219], v174 offset:19200
	ds_read_b128 v[220:223], v174 offset:64
	ds_read_b128 v[224:227], v174 offset:6464
	s_add_i32 s4, s30, 63
	s_cmp_le_i32 s4, s21
	s_waitcnt lgkmcnt(5)
	v_mfma_f32_16x16x32_bf16 v[132:135], v[170:173], v[104:107], 0
	v_mfma_f32_16x16x32_bf16 v[148:151], v[170:173], v[108:111], 0
	ds_read_b128 v[170:173], v174 offset:12864
	s_waitcnt lgkmcnt(5)
	v_mfma_f32_16x16x32_bf16 v[136:139], v[208:211], v[104:107], 0
	v_mfma_f32_16x16x32_bf16 v[156:159], v[208:211], v[108:111], 0
	ds_read_b128 v[208:211], v174 offset:19264
	s_waitcnt lgkmcnt(5)
	v_mfma_f32_16x16x32_bf16 v[140:143], v[212:215], v[104:107], 0
	v_mfma_f32_16x16x32_bf16 v[152:155], v[212:215], v[108:111], 0
	ds_read_b128 v[212:215], v174 offset:128
	s_waitcnt lgkmcnt(5)
	v_mfma_f32_16x16x32_bf16 v[144:147], v[216:219], v[104:107], 0
	v_mfma_f32_16x16x32_bf16 v[160:163], v[216:219], v[108:111], 0
	ds_read_b128 v[216:219], v174 offset:6528
	s_waitcnt lgkmcnt(5)
	v_mfma_f32_16x16x32_bf16 v[132:135], v[220:223], v[92:95], v[132:135]
	v_mfma_f32_16x16x32_bf16 v[148:151], v[220:223], v[100:103], v[148:151]
	ds_read_b128 v[220:223], v174 offset:12928
	s_waitcnt lgkmcnt(5)
	v_mfma_f32_16x16x32_bf16 v[136:139], v[224:227], v[92:95], v[136:139]
	v_mfma_f32_16x16x32_bf16 v[156:159], v[224:227], v[100:103], v[156:159]
	ds_read_b128 v[224:227], v174 offset:19328
	s_waitcnt lgkmcnt(5)
	v_mfma_f32_16x16x32_bf16 v[140:143], v[170:173], v[92:95], v[140:143]
	v_mfma_f32_16x16x32_bf16 v[152:155], v[170:173], v[100:103], v[152:155]
	ds_read_b128 v[170:173], v174 offset:192
	s_waitcnt lgkmcnt(5)
	v_mfma_f32_16x16x32_bf16 v[144:147], v[208:211], v[92:95], v[144:147]
	v_mfma_f32_16x16x32_bf16 v[160:163], v[208:211], v[100:103], v[160:163]
	ds_read_b128 v[208:211], v174 offset:6592
	s_waitcnt lgkmcnt(5)
	v_mfma_f32_16x16x32_bf16 v[132:135], v[212:215], v[88:91], v[132:135]
	v_mfma_f32_16x16x32_bf16 v[148:151], v[212:215], v[96:99], v[148:151]
	ds_read_b128 v[212:215], v174 offset:12992
	s_waitcnt lgkmcnt(5)
	v_mfma_f32_16x16x32_bf16 v[136:139], v[216:219], v[88:91], v[136:139]
	v_mfma_f32_16x16x32_bf16 v[156:159], v[216:219], v[96:99], v[156:159]
	ds_read_b128 v[216:219], v174 offset:19392
	s_waitcnt lgkmcnt(5)
	v_mfma_f32_16x16x32_bf16 v[140:143], v[220:223], v[88:91], v[140:143]
	v_mfma_f32_16x16x32_bf16 v[152:155], v[220:223], v[96:99], v[152:155]
	ds_read_b128 v[220:223], v174 offset:256
	s_waitcnt lgkmcnt(5)
	v_mfma_f32_16x16x32_bf16 v[144:147], v[224:227], v[88:91], v[144:147]
	v_mfma_f32_16x16x32_bf16 v[160:163], v[224:227], v[96:99], v[160:163]
	ds_read_b128 v[224:227], v174 offset:6656
	s_waitcnt lgkmcnt(5)
	v_mfma_f32_16x16x32_bf16 v[132:135], v[170:173], v[76:79], v[132:135]
	v_mfma_f32_16x16x32_bf16 v[148:151], v[170:173], v[84:87], v[148:151]
	ds_read_b128 v[170:173], v174 offset:13056
	s_waitcnt lgkmcnt(5)
	v_mfma_f32_16x16x32_bf16 v[136:139], v[208:211], v[76:79], v[136:139]
	v_mfma_f32_16x16x32_bf16 v[156:159], v[208:211], v[84:87], v[156:159]
	ds_read_b128 v[208:211], v174 offset:19456
	s_waitcnt lgkmcnt(5)
	v_mfma_f32_16x16x32_bf16 v[140:143], v[212:215], v[76:79], v[140:143]
	v_mfma_f32_16x16x32_bf16 v[152:155], v[212:215], v[84:87], v[152:155]
	ds_read_b128 v[212:215], v174 offset:320
	s_waitcnt lgkmcnt(5)
	v_mfma_f32_16x16x32_bf16 v[144:147], v[216:219], v[76:79], v[144:147]
	v_mfma_f32_16x16x32_bf16 v[160:163], v[216:219], v[84:87], v[160:163]
	ds_read_b128 v[216:219], v174 offset:6720
	s_waitcnt lgkmcnt(5)
	v_mfma_f32_16x16x32_bf16 v[132:135], v[220:223], v[72:75], v[132:135]
	v_mfma_f32_16x16x32_bf16 v[148:151], v[220:223], v[80:83], v[148:151]
	ds_read_b128 v[220:223], v174 offset:13120
	s_waitcnt lgkmcnt(5)
	v_mfma_f32_16x16x32_bf16 v[136:139], v[224:227], v[72:75], v[136:139]
	v_mfma_f32_16x16x32_bf16 v[156:159], v[224:227], v[80:83], v[156:159]
	ds_read_b128 v[224:227], v174 offset:19520
	s_waitcnt lgkmcnt(5)
	v_mfma_f32_16x16x32_bf16 v[140:143], v[170:173], v[72:75], v[140:143]
	v_mfma_f32_16x16x32_bf16 v[152:155], v[170:173], v[80:83], v[152:155]
	s_waitcnt lgkmcnt(4)
	v_mfma_f32_16x16x32_bf16 v[144:147], v[208:211], v[72:75], v[144:147]
	v_mfma_f32_16x16x32_bf16 v[160:163], v[208:211], v[80:83], v[160:163]
	s_waitcnt lgkmcnt(3)
	v_mfma_f32_16x16x32_bf16 v[132:135], v[212:215], v[64:67], v[132:135]
	v_mfma_f32_16x16x32_bf16 v[148:151], v[212:215], v[68:71], v[148:151]
	s_waitcnt lgkmcnt(2)
	v_mfma_f32_16x16x32_bf16 v[136:139], v[216:219], v[64:67], v[136:139]
	v_mfma_f32_16x16x32_bf16 v[156:159], v[216:219], v[68:71], v[156:159]
	s_waitcnt lgkmcnt(1)
	v_mfma_f32_16x16x32_bf16 v[140:143], v[220:223], v[64:67], v[140:143]
	v_mfma_f32_16x16x32_bf16 v[152:155], v[220:223], v[68:71], v[152:155]
	s_waitcnt lgkmcnt(0)
	v_mfma_f32_16x16x32_bf16 v[144:147], v[224:227], v[64:67], v[144:147]
	v_mfma_f32_16x16x32_bf16 v[160:163], v[224:227], v[68:71], v[160:163]
	s_cbranch_scc1 .LBB0_144
; __device__ __forceinline__ void attn_phase(LAS unsigned char* lds, const bf16_t* Q, const bf16_t* KN, const bf16_t* P, const bf16_t* VT, bf16_t* CAT, int bid, int G, const int tid) {
;     ...
;                 if (kt * 64 + 63 > qlo) {
; #pragma unroll
;                     for (int kb = 0; kb < 4; ++kb)
; #pragma unroll
;                         for (int qi = 0; qi < 2; ++qi)
; #pragma unroll
;                             for (int j = 0; j < 4; ++j) { const int key = kt * 64 + kb * 16 + fq * 4 + j, q = qlo + qi * 16 + fr; if (key > q) s[kb][qi][j] = -INFINITY; }
;                 }
	v_add_u32_e32 v171, s30, v242
	v_cmp_gt_i32_e32 vcc, v171, v244
	v_mov_b32_e32 v170, s78
	v_cmp_lt_i32_e64 s[4:5], v171, v244
	v_cndmask_b32_e32 v170, v132, v170, vcc
	v_add_u32_e32 v172, 2, v171
	v_cndmask_b32_e64 v132, v170, v132, s[4:5]
	v_cndmask_b32_e64 v133, v234, v133, s[4:5]
	v_cmp_le_i32_e64 s[4:5], v172, v244
	v_add_u32_e32 v173, 3, v171
	v_mov_b32_e32 v170, s78
	v_cndmask_b32_e64 v134, v234, v134, s[4:5]
	v_cmp_le_i32_e64 s[4:5], v173, v244
	v_add_u32_e32 v174, 19, v171
	v_add_u32_e32 v175, 35, v171
	v_cndmask_b32_e64 v135, v234, v135, s[4:5]
	v_cmp_gt_i32_e64 s[4:5], v171, v199
	s_nop 1
	v_cndmask_b32_e64 v170, v148, v170, s[4:5]
	v_cmp_lt_i32_e64 s[4:5], v171, v199
	s_nop 1
	v_cndmask_b32_e64 v148, v170, v148, s[4:5]
	v_cndmask_b32_e64 v149, v234, v149, s[4:5]
	v_cmp_le_i32_e64 s[4:5], v172, v199
	v_add_u32_e32 v170, 16, v171
	v_add_u32_e32 v172, 17, v171
	v_cndmask_b32_e64 v150, v234, v150, s[4:5]
	v_cmp_le_i32_e64 s[4:5], v173, v199
	v_add_u32_e32 v173, 18, v171
	s_nop 0
	v_cndmask_b32_e64 v151, v234, v151, s[4:5]
	v_cmp_gt_i32_e64 s[4:5], v170, v244
	v_mov_b32_e32 v170, s78
	v_cndmask_b32_e32 v156, v156, v170, vcc
	v_cmp_le_i32_e32 vcc, v172, v199
	v_cndmask_b32_e64 v136, v136, v170, s[4:5]
	v_cmp_le_i32_e64 s[4:5], v172, v244
	v_cndmask_b32_e32 v157, v234, v157, vcc
	v_cmp_le_i32_e32 vcc, v173, v199
	v_add_u32_e32 v172, 32, v171
	v_cndmask_b32_e64 v137, v234, v137, s[4:5]
	v_cndmask_b32_e32 v158, v234, v158, vcc
	v_cmp_le_i32_e32 vcc, v174, v199
	v_cmp_le_i32_e64 s[4:5], v173, v244
	v_add_u32_e32 v173, 33, v171
	v_cndmask_b32_e32 v159, v234, v159, vcc
	v_cmp_gt_i32_e32 vcc, v172, v244
	v_cndmask_b32_e64 v138, v234, v138, s[4:5]
	v_cmp_le_i32_e64 s[4:5], v174, v244
	v_cndmask_b32_e32 v140, v140, v170, vcc
	v_cmp_le_i32_e32 vcc, v173, v244
	v_add_u32_e32 v174, 34, v171
	v_cndmask_b32_e64 v139, v234, v139, s[4:5]
	v_cndmask_b32_e32 v141, v234, v141, vcc
	v_cmp_le_i32_e32 vcc, v174, v244
	s_nop 1
	v_cndmask_b32_e32 v142, v234, v142, vcc
	v_cmp_le_i32_e32 vcc, v175, v244
	s_nop 1
	v_cndmask_b32_e32 v143, v234, v143, vcc
	v_cmp_gt_i32_e32 vcc, v172, v199
	v_add_u32_e32 v172, 48, v171
	s_nop 0
	v_cndmask_b32_e32 v152, v152, v170, vcc
	v_cmp_le_i32_e32 vcc, v173, v199
	v_add_u32_e32 v173, 49, v171
	s_nop 0
	v_cndmask_b32_e32 v153, v234, v153, vcc
	v_cmp_le_i32_e32 vcc, v174, v199
	v_add_u32_e32 v174, 50, v171
	v_add_u32_e32 v171, 51, v171
	v_cndmask_b32_e32 v154, v234, v154, vcc
	v_cmp_le_i32_e32 vcc, v175, v199
	s_nop 1
	v_cndmask_b32_e32 v155, v234, v155, vcc
	v_cmp_gt_i32_e32 vcc, v172, v244
	s_nop 1
	v_cndmask_b32_e32 v144, v144, v170, vcc
	v_cmp_le_i32_e32 vcc, v173, v244
	s_nop 1
	v_cndmask_b32_e32 v145, v234, v145, vcc
	v_cmp_le_i32_e32 vcc, v174, v244
	s_nop 1
	v_cndmask_b32_e32 v146, v234, v146, vcc
	v_cmp_le_i32_e32 vcc, v171, v244
	s_nop 1
	v_cndmask_b32_e32 v147, v234, v147, vcc
	v_cmp_gt_i32_e32 vcc, v172, v199
	s_nop 1
	v_cndmask_b32_e32 v160, v160, v170, vcc
	v_cmp_le_i32_e32 vcc, v173, v199
	s_nop 1
	v_cndmask_b32_e32 v161, v234, v161, vcc
	v_cmp_le_i32_e32 vcc, v174, v199
	s_nop 1
	v_cndmask_b32_e32 v162, v234, v162, vcc
	v_cmp_le_i32_e32 vcc, v171, v199
	s_nop 1
	v_cndmask_b32_e32 v163, v234, v163, vcc
	s_branch .LBB0_144
